# adds non-temporal loads for the last-use input rows (layer-0 post pass and prologue) to v41
# speedup vs baseline: 1.0097x; 1.0037x over previous
; #define GAS __attribute__((address_space(1)))
; DI float bf_lo(unsigned u) { return __uint_as_float(u << 16); }
; DI float bf_hi(unsigned u) { return __uint_as_float(u & 0xffff0000u); }
; DI void post_pass(int wv, const bf16_t* raw, long raw_row0, float* x, const float* gpost, const float* gpre, bf16_t* XN, int row_lo, int row_hi, const float* xin_p = nullptr, const float* xin_s = nullptr) {
;     ...
;     for (int row = row_lo + gw; row < row_hi; row += 2 * NGW) {
;         f32x4 v[2][4], xv[2][4]; float s[2] = {0.f, 0.f};
; #pragma unroll
;         for (int q = 0; q < 2; ++q) { const int rw = row + q * NGW;
;             const GAS u32x2* rr = (const GAS u32x2*)(raw + (size_t)(rw - raw_row0) * DM) + lane;
;             const GAS f32x4* xr = (const GAS f32x4*)(xin_p ? (rw < TOK_P ? xin_p + (size_t)rw * DM : xin_s + (size_t)(rw - TOK_P) * DM) : x + (size_t)rw * DM) + lane;
; #pragma unroll
;             for (int j = 0; j < 4; ++j) { const u32x2 w = rr[64 * j]; v[q][j] = (f32x4){bf_lo(w.x), bf_hi(w.x), bf_lo(w.y), bf_hi(w.y)}; xv[q][j] = xr[64 * j]; } }
; #pragma unroll
;         for (int q = 0; q < 2; ++q)
; #pragma unroll
;             for (int j = 0; j < 4; ++j) s[q] += (v[q][j].x * v[q][j].x + v[q][j].y * v[q][j].y) + (v[q][j].z * v[q][j].z + v[q][j].w * v[q][j].w);
; #pragma unroll
;         for (int q = 0; q < 2; ++q) { const int rw = row + q * NGW; GAS f32x4* xr = (GAS f32x4*)(x + (size_t)rw * DM) + lane;
;             const float rstd = __builtin_amdgcn_rsqf(wave_sum(s[q], lane) * (1.0f / DM) + RMS_EPS);
; #pragma unroll
;             for (int j = 0; j < 4; ++j) { const f32x4 gg = ((const GAS f32x4*)gpost)[lane + 64 * j]; xv[q][j] = xv[q][j] + v[q][j] * rstd * gg; xr[64 * j] = xv[q][j]; }
.LBB0_525:
	s_ashr_i32 s17, s16, 31
	s_lshl_b64 s[6:7], s[16:17], 11
	s_add_u32 s6, s22, s6
	s_addc_u32 s7, s23, s7
	v_lshlrev_b32_e32 v57, 3, v32
	global_load_dwordx2 v[0:1], v57, s[6:7] offset:1536 nt
	global_load_dwordx2 v[2:3], v57, s[6:7] nt
	global_load_dwordx2 v[4:5], v57, s[6:7] offset:512 nt
	global_load_dwordx2 v[6:7], v57, s[6:7] offset:1024 nt
	s_add_i32 s26, s16, 0xffffc000
	s_cmpk_lt_i32 s16, 0x4000
	s_cselect_b64 s[6:7], -1, 0
	s_and_b64 s[14:15], s[6:7], exec
	s_cselect_b32 s27, s8, s21
	s_cselect_b32 s28, s9, s20
	s_or_b64 s[6:7], s[10:11], s[6:7]
	s_and_b64 s[6:7], s[6:7], exec
	s_cselect_b32 s7, s17, 0
	s_cselect_b32 s6, s16, s26
	s_and_b64 s[14:15], s[10:11], exec
	global_load_dwordx4 v[16:19], v[36:37], off
	s_cselect_b32 s14, s18, s28
	s_cselect_b32 s15, s19, s27
	s_lshl_b64 s[6:7], s[6:7], 12
	s_add_u32 s6, s15, s6
	v_lshlrev_b32_e32 v58, 4, v32
	s_addc_u32 s7, s14, s7
	global_load_dwordx4 v[24:27], v58, s[6:7] nt
	global_load_dwordx4 v[60:63], v58, s[6:7] offset:1024 nt
	global_load_dwordx4 v[64:67], v58, s[6:7] offset:2048 nt
	global_load_dwordx4 v[20:23], v58, s[6:7] offset:3072 nt
	s_add_i32 s14, s16, s72
	s_ashr_i32 s15, s14, 31
	s_lshl_b64 s[6:7], s[14:15], 11
	s_add_u32 s6, s22, s6
	s_addc_u32 s7, s23, s7
	s_add_i32 s28, s14, 0xffffc000
	s_cmpk_lt_i32 s14, 0x4000
	global_load_dwordx2 v[44:45], v57, s[6:7] nt
	global_load_dwordx2 v[42:43], v57, s[6:7] offset:512 nt
	global_load_dwordx2 v[40:41], v57, s[6:7] offset:1024 nt
	global_load_dwordx2 v[38:39], v57, s[6:7] offset:1536 nt
	s_cselect_b64 s[6:7], -1, 0
	s_and_b64 s[26:27], s[6:7], exec
	s_cselect_b32 s29, s8, s21
	s_cselect_b32 s30, s9, s20
	s_or_b64 s[6:7], s[10:11], s[6:7]
	s_and_b64 s[6:7], s[6:7], exec
	s_cselect_b32 s7, s15, 0
	s_cselect_b32 s6, s14, s28
	s_and_b64 s[26:27], s[10:11], exec
	s_cselect_b32 s26, s18, s30
	s_cselect_b32 s27, s19, s29
	s_lshl_b64 s[6:7], s[6:7], 12
	s_add_u32 s6, s27, s6
	s_addc_u32 s7, s26, s7
	s_lshl_b64 s[26:27], s[16:17], 12
	s_add_u32 s26, s19, s26
	s_addc_u32 s27, s18, s27
	v_cndmask_b32_e64 v46, 0, 1, s[12:13]
	s_andn2_b64 vcc, exec, s[12:13]
	s_waitcnt vmcnt(0)
	v_lshlrev_b32_e32 v49, 16, v0
	v_and_b32_e32 v29, 0xffff0000, v2
	v_and_b32_e32 v31, 0xffff0000, v3
	v_and_b32_e32 v47, 0xffff0000, v0
	v_lshlrev_b32_e32 v50, 16, v1
	v_and_b32_e32 v51, 0xffff0000, v1
	v_lshlrev_b32_e32 v28, 16, v2
	v_lshlrev_b32_e32 v30, 16, v3
	v_lshlrev_b32_e32 v68, 16, v4
	v_and_b32_e32 v71, 0xffff0000, v5
	v_and_b32_e32 v70, 0xffff0000, v4
	v_mul_f32_e32 v0, v31, v31
	v_mul_f32_e32 v4, v29, v29
	v_mov_b32_e32 v1, v49
	v_lshlrev_b32_e32 v69, 16, v5
	v_and_b32_e32 v73, 0xffff0000, v6
	v_and_b32_e32 v75, 0xffff0000, v7
	v_pk_mul_f32 v[2:3], v[70:71], v[70:71]
	v_pk_fma_f32 v[10:11], v[30:31], v[30:31], v[0:1] op_sel_hi:[1,1,0]
	v_pk_fma_f32 v[4:5], v[28:29], v[28:29], v[4:5] op_sel_hi:[1,1,0]
	v_lshlrev_b32_e32 v72, 16, v6
	v_lshlrev_b32_e32 v74, 16, v7
	v_mul_f32_e32 v6, v73, v73
	v_mul_f32_e32 v8, v75, v75
	v_pk_fma_f32 v[2:3], v[68:69], v[68:69], v[2:3]
	v_mov_b32_e32 v48, v4
	v_mov_b32_e32 v0, v10
	v_mul_f32_e32 v12, v47, v47
	v_mul_f32_e32 v13, v50, v50
	v_mul_f32_e32 v14, v51, v51
	v_pk_fma_f32 v[6:7], v[72:73], v[72:73], v[6:7] op_sel_hi:[1,1,0]
	v_pk_fma_f32 v[8:9], v[74:75], v[74:75], v[8:9] op_sel_hi:[1,1,0]
	v_pk_add_f32 v[4:5], v[4:5], v[10:11]
	v_pk_add_f32 v[2:3], v[2:3], v[2:3] op_sel:[0,1] op_sel_hi:[1,0]
	v_pk_mul_f32 v[0:1], v[48:49], v[0:1]
	v_mov_b32_e32 v7, v13
	v_mov_b32_e32 v9, v14
	v_mov_b32_e32 v3, v12
	v_mov_b32_e32 v5, v1
	v_pk_add_f32 v[6:7], v[6:7], v[8:9]
	v_pk_add_f32 v[0:1], v[4:5], v[2:3]
	global_load_dwordx4 v[12:15], v58, s[6:7] nt
	global_load_dwordx4 v[8:11], v58, s[6:7] offset:1024 nt
	v_pk_add_f32 v[0:1], v[0:1], v[6:7]
	s_nop 0
	v_add_f32_e32 v0, v0, v1
	ds_bpermute_b32 v1, v33, v0
	s_waitcnt lgkmcnt(0)
	v_add_f32_e32 v0, v0, v1
	ds_bpermute_b32 v1, v52, v0
	s_waitcnt lgkmcnt(0)
	v_add_f32_e32 v0, v0, v1
	ds_bpermute_b32 v1, v53, v0
	s_waitcnt lgkmcnt(0)
	v_add_f32_e32 v0, v0, v1
	ds_bpermute_b32 v1, v54, v0
	s_waitcnt lgkmcnt(0)
	v_add_f32_e32 v0, v0, v1
	ds_bpermute_b32 v1, v55, v0
	s_waitcnt lgkmcnt(0)
	v_add_f32_e32 v0, v0, v1
	ds_bpermute_b32 v1, v56, v0
	s_waitcnt lgkmcnt(0)
	v_add_f32_e32 v0, v0, v1
	v_fmamk_f32 v0, v0, 0x3a800000, v174
	v_rsq_f32_e32 v48, v0
	global_load_dwordx4 v[4:7], v58, s[6:7] offset:2048 nt
	global_load_dwordx4 v[0:3], v58, s[6:7] offset:3072 nt
	v_cmp_ne_u32_e64 s[6:7], 1, v46
	v_mov_b32_e32 v46, v49
	v_pk_mul_f32 v[28:29], v[48:49], v[28:29] op_sel_hi:[0,1]
	v_pk_mul_f32 v[30:31], v[48:49], v[30:31] op_sel_hi:[0,1]
	v_pk_fma_f32 v[30:31], v[18:19], v[30:31], v[26:27]
	v_pk_fma_f32 v[28:29], v[16:17], v[28:29], v[24:25]
	global_store_dwordx4 v58, v[28:31], s[26:27]
	global_load_dwordx4 v[16:19], v[36:37], off offset:1024
	v_mov_b32_e32 v24, v69
	v_mov_b32_e32 v25, v71
	v_mov_b32_e32 v69, v70
	v_pk_mul_f32 v[26:27], v[48:49], v[24:25] op_sel_hi:[0,1]
	v_pk_mul_f32 v[24:25], v[48:49], v[68:69] op_sel_hi:[0,1]
	v_pk_mul_f32 v[50:51], v[48:49], v[50:51] op_sel_hi:[0,1]
	v_pk_mul_f32 v[46:47], v[48:49], v[46:47] op_sel_hi:[0,1]
	s_waitcnt vmcnt(0)
	v_pk_fma_f32 v[24:25], v[16:17], v[24:25], v[60:61]
	v_pk_fma_f32 v[26:27], v[18:19], v[26:27], v[62:63]
	global_store_dwordx4 v58, v[24:27], s[26:27] offset:1024
	global_load_dwordx4 v[16:19], v[36:37], off offset:2048
	v_pk_mul_f32 v[60:61], v[48:49], v[74:75] op_sel_hi:[0,1]
	v_pk_mul_f32 v[62:63], v[48:49], v[72:73] op_sel_hi:[0,1]
	s_waitcnt vmcnt(0)
	v_pk_fma_f32 v[16:17], v[16:17], v[62:63], v[64:65]
	v_pk_fma_f32 v[18:19], v[18:19], v[60:61], v[66:67]
	global_store_dwordx4 v58, v[16:19], s[26:27] offset:2048
	global_load_dwordx4 v[60:63], v[36:37], off offset:3072
	s_waitcnt vmcnt(0)
	v_pk_fma_f32 v[20:21], v[60:61], v[46:47], v[20:21]
	v_pk_fma_f32 v[22:23], v[62:63], v[50:51], v[22:23]
	global_store_dwordx4 v58, v[20:23], s[26:27] offset:3072
	s_cbranch_vccnz .LBB0_527
; #define GAS __attribute__((address_space(1)))
; DI unsigned pk2(float lo, float hi) { f32x2 v = {lo, hi}; bf16x2_t b = __builtin_convertvector(v, bf16x2_t); return __builtin_bit_cast(unsigned, b); }
; DI void norm_row_bf16(const f32x4 (&v)[4], const float* g, bf16_t* orow, int lane) {
;     float s = 0.f;
; #pragma unroll
;     for (int j = 0; j < 4; ++j) s += (v[j].x * v[j].x + v[j].y * v[j].y) + (v[j].z * v[j].z + v[j].w * v[j].w);
;     const float rstd = __builtin_amdgcn_rsqf(wave_sum(s, lane) * (1.0f / DM) + RMS_EPS);
;     GAS u32x2* o8 = (GAS u32x2*)orow + lane;
; #pragma unroll
;     for (int j = 0; j < 4; ++j) { const f32x4 gg = ((const GAS f32x4*)g)[lane + 64 * j]; u32x2 w; w.x = pk2(v[j].x * rstd * gg.x, v[j].y * rstd * gg.y); w.y = pk2(v[j].z * rstd * gg.z, v[j].w * rstd * gg.w); o8[64 * j] = w; }
; }
	v_pk_mul_f32 v[46:47], v[30:31], v[30:31]
	v_pk_mul_f32 v[48:49], v[28:29], v[28:29]
	s_lshl_b64 s[16:17], s[16:17], 10
	v_pk_mov_b32 v[50:51], v[48:49], v[46:47] op_sel:[1,0]
	v_mov_b32_e32 v49, v47
	v_pk_add_f32 v[46:47], v[50:51], v[48:49]
	v_pk_mul_f32 v[48:49], v[26:27], v[26:27]
	v_pk_add_f32 v[46:47], v[46:47], v[46:47] op_sel_hi:[0,1]
	v_pk_mul_f32 v[50:51], v[24:25], v[24:25]
	v_mul_f32_e32 v46, v16, v16
	v_pk_mov_b32 v[60:61], v[50:51], v[48:49] op_sel:[1,0]
	v_mov_b32_e32 v51, v49
	v_pk_add_f32 v[48:49], v[60:61], v[50:51]
	v_pk_fma_f32 v[50:51], v[16:17], v[16:17], v[46:47] op_sel_hi:[1,1,0]
	v_mul_f32_e32 v46, v18, v18
	v_pk_add_f32 v[48:49], v[48:49], v[48:49] op_sel_hi:[0,1]
	v_pk_fma_f32 v[60:61], v[18:19], v[18:19], v[46:47] op_sel_hi:[1,1,0]
	v_mul_f32_e32 v50, v20, v20
	v_mul_f32_e32 v60, v21, v21
	v_mul_f32_e32 v46, v22, v22
	v_mul_f32_e32 v48, v23, v23
	v_pk_add_f32 v[50:51], v[50:51], v[60:61]
	v_pk_add_f32 v[46:47], v[46:47], v[48:49]
	s_lshl_b64 s[16:17], s[16:17], 1
	v_pk_add_f32 v[46:47], v[50:51], v[46:47]
	global_load_dwordx4 v[48:51], v[34:35], off
	v_add_f32_e32 v46, v46, v47
	ds_bpermute_b32 v47, v33, v46
	s_add_u32 s16, s24, s16
	s_addc_u32 s17, s25, s17
	s_waitcnt lgkmcnt(0)
	v_add_f32_e32 v46, v46, v47
	ds_bpermute_b32 v47, v52, v46
	s_waitcnt lgkmcnt(0)
	v_add_f32_e32 v46, v46, v47
	ds_bpermute_b32 v47, v53, v46
	s_waitcnt lgkmcnt(0)
	v_add_f32_e32 v46, v46, v47
	ds_bpermute_b32 v47, v54, v46
	s_waitcnt lgkmcnt(0)
	v_add_f32_e32 v46, v46, v47
	ds_bpermute_b32 v47, v55, v46
	s_waitcnt lgkmcnt(0)
	v_add_f32_e32 v46, v46, v47
	ds_bpermute_b32 v47, v56, v46
	s_waitcnt lgkmcnt(0)
	v_add_f32_e32 v46, v46, v47
	v_fmamk_f32 v46, v46, 0x3a800000, v174
	v_rsq_f32_e32 v46, v46
	s_nop 0
	v_pk_mul_f32 v[28:29], v[28:29], v[46:47] op_sel_hi:[1,0]
	v_pk_mul_f32 v[30:31], v[30:31], v[46:47] op_sel_hi:[1,0]
	v_pk_mul_f32 v[24:25], v[24:25], v[46:47] op_sel_hi:[1,0]
	v_pk_mul_f32 v[26:27], v[26:27], v[46:47] op_sel_hi:[1,0]
	v_pk_mul_f32 v[16:17], v[16:17], v[46:47] op_sel_hi:[1,0]
	v_pk_mul_f32 v[18:19], v[18:19], v[46:47] op_sel_hi:[1,0]
	v_pk_mul_f32 v[20:21], v[20:21], v[46:47] op_sel_hi:[1,0]
	s_waitcnt vmcnt(0)
	v_pk_mul_f32 v[28:29], v[48:49], v[28:29]
	v_pk_mul_f32 v[30:31], v[50:51], v[30:31]
	v_cvt_pk_bf16_f32 v28, v28, v29
	v_cvt_pk_bf16_f32 v29, v30, v31
	global_store_dwordx2 v57, v[28:29], s[16:17]
	global_load_dwordx4 v[28:31], v[34:35], off offset:1024
	s_waitcnt vmcnt(0)
	v_pk_mul_f32 v[24:25], v[28:29], v[24:25]
	v_pk_mul_f32 v[26:27], v[30:31], v[26:27]
	v_cvt_pk_bf16_f32 v24, v24, v25
	v_cvt_pk_bf16_f32 v25, v26, v27
	global_store_dwordx2 v57, v[24:25], s[16:17] offset:512
	global_load_dwordx4 v[24:27], v[34:35], off offset:2048
	s_waitcnt vmcnt(0)
	v_pk_mul_f32 v[16:17], v[24:25], v[16:17]
	v_pk_mul_f32 v[18:19], v[26:27], v[18:19]
	v_cvt_pk_bf16_f32 v16, v16, v17
	v_cvt_pk_bf16_f32 v17, v18, v19
	global_store_dwordx2 v57, v[16:17], s[16:17] offset:1024
	global_load_dwordx4 v[16:19], v[34:35], off offset:3072
	s_waitcnt vmcnt(0)
	v_pk_mul_f32 v[16:17], v[20:21], v[16:17]
	v_pk_mul_f32 v[20:21], v[22:23], v[46:47] op_sel_hi:[1,0]
	v_cvt_pk_bf16_f32 v16, v16, v17
	v_pk_mul_f32 v[18:19], v[20:21], v[18:19]
	s_nop 0
	v_cvt_pk_bf16_f32 v17, v18, v19
	global_store_dwordx2 v57, v[16:17], s[16:17] offset:1536

; #define GAS __attribute__((address_space(1)))
; DI unsigned pk2(float lo, float hi) { f32x2 v = {lo, hi}; bf16x2_t b = __builtin_convertvector(v, bf16x2_t); return __builtin_bit_cast(unsigned, b); }
; DI void norm_row_bf16(const f32x4 (&v)[4], const float* g, bf16_t* orow, int lane) {
;     float s = 0.f;
; #pragma unroll
;     for (int j = 0; j < 4; ++j) s += (v[j].x * v[j].x + v[j].y * v[j].y) + (v[j].z * v[j].z + v[j].w * v[j].w);
;     const float rstd = __builtin_amdgcn_rsqf(wave_sum(s, lane) * (1.0f / DM) + RMS_EPS);
;     GAS u32x2* o8 = (GAS u32x2*)orow + lane;
; #pragma unroll
;     for (int j = 0; j < 4; ++j) { const f32x4 gg = ((const GAS f32x4*)g)[lane + 64 * j]; u32x2 w; w.x = pk2(v[j].x * rstd * gg.x, v[j].y * rstd * gg.y); w.y = pk2(v[j].z * rstd * gg.z, v[j].w * rstd * gg.w); o8[64 * j] = w; }
; }
; __global__ void __launch_bounds__(512) fwd_megakernel(Params p) {
;     ...
;             for (int row = gw; row < 1536; row += NGW) { const float* src = row < 1024 ? mem_p + (size_t)row * DM : mem_s + (size_t)(row - 1024) * DM;
;                 f32x4 v[4];
; #pragma unroll
;                 for (int j = 0; j < 4; ++j) v[j] = ((const GAS f32x4*)src)[lane + 64 * j];
;                 norm_row_bf16(v, g_mem, memn + (size_t)row * DM, lane); }
.LBB0_1061:
	v_lshlrev_b32_e32 v0, 4, v16
	global_load_dwordx4 v[12:15], v0, s[12:13] nt
	global_load_dwordx4 v[8:11], v0, s[12:13] offset:1024 nt
	global_load_dwordx4 v[4:7], v0, s[12:13] offset:2048 nt
	s_nop 0
	global_load_dwordx4 v[0:3], v0, s[12:13] offset:3072 nt
	s_lshl_b64 s[12:13], s[14:15], 11
	s_add_u32 s12, s1, s12
	s_addc_u32 s13, s16, s13
	s_add_u32 s10, s10, s72
	s_addc_u32 s11, s11, s73
	s_waitcnt vmcnt(0)
	v_pk_mul_f32 v[28:29], v[14:15], v[14:15]
	v_pk_mul_f32 v[30:31], v[12:13], v[12:13]
	v_mul_f32_e32 v22, v4, v4
	v_pk_mov_b32 v[32:33], v[30:31], v[28:29] op_sel:[1,0]
	v_mov_b32_e32 v31, v29
	v_pk_add_f32 v[28:29], v[32:33], v[30:31]
	v_pk_mul_f32 v[30:31], v[10:11], v[10:11]
	v_pk_mul_f32 v[32:33], v[8:9], v[8:9]
	v_pk_add_f32 v[28:29], v[28:29], v[28:29] op_sel_hi:[0,1]
	v_pk_mov_b32 v[34:35], v[32:33], v[30:31] op_sel:[1,0]
	v_mov_b32_e32 v33, v31
	v_pk_add_f32 v[30:31], v[34:35], v[32:33]
	v_pk_fma_f32 v[32:33], v[4:5], v[4:5], v[22:23] op_sel_hi:[1,1,0]
	v_mul_f32_e32 v22, v6, v6
	v_pk_add_f32 v[30:31], v[30:31], v[30:31] op_sel_hi:[0,1]
	v_pk_fma_f32 v[34:35], v[6:7], v[6:7], v[22:23] op_sel_hi:[1,1,0]
	v_mul_f32_e32 v32, v0, v0
	v_mul_f32_e32 v34, v1, v1
	v_mul_f32_e32 v28, v2, v2
	v_mul_f32_e32 v30, v3, v3
	v_pk_add_f32 v[32:33], v[32:33], v[34:35]
	v_pk_add_f32 v[28:29], v[28:29], v[30:31]
	s_nop 0
	v_pk_add_f32 v[28:29], v[32:33], v[28:29]
	v_lshlrev_b32_e32 v32, 3, v16
	v_add_f32_e32 v22, v28, v29
	ds_bpermute_b32 v28, v19, v22
	s_waitcnt lgkmcnt(0)
	v_add_f32_e32 v22, v22, v28
	ds_bpermute_b32 v28, v23, v22
	s_waitcnt lgkmcnt(0)
	v_add_f32_e32 v22, v22, v28
	ds_bpermute_b32 v28, v24, v22
	s_waitcnt lgkmcnt(0)
	v_add_f32_e32 v22, v22, v28
	ds_bpermute_b32 v28, v25, v22
	s_waitcnt lgkmcnt(0)
	v_add_f32_e32 v22, v22, v28
	ds_bpermute_b32 v28, v26, v22
	s_waitcnt lgkmcnt(0)
	v_add_f32_e32 v22, v22, v28
	ds_bpermute_b32 v28, v27, v22
	s_waitcnt lgkmcnt(0)
	v_add_f32_e32 v22, v22, v28
	global_load_dwordx4 v[28:31], v[20:21], off
	v_fmamk_f32 v22, v22, 0x3a800000, v174
	v_rsq_f32_e32 v22, v22
	s_nop 0
	v_pk_mul_f32 v[12:13], v[12:13], v[22:23] op_sel_hi:[1,0]
	v_pk_mul_f32 v[14:15], v[14:15], v[22:23] op_sel_hi:[1,0]
	v_pk_mul_f32 v[8:9], v[8:9], v[22:23] op_sel_hi:[1,0]
	v_pk_mul_f32 v[10:11], v[10:11], v[22:23] op_sel_hi:[1,0]
	v_pk_mul_f32 v[4:5], v[4:5], v[22:23] op_sel_hi:[1,0]
	v_pk_mul_f32 v[6:7], v[6:7], v[22:23] op_sel_hi:[1,0]
	v_pk_mul_f32 v[0:1], v[0:1], v[22:23] op_sel_hi:[1,0]
	v_pk_mul_f32 v[2:3], v[2:3], v[22:23] op_sel_hi:[1,0]
	s_waitcnt vmcnt(0)
	v_pk_mul_f32 v[12:13], v[28:29], v[12:13]
	v_pk_mul_f32 v[14:15], v[30:31], v[14:15]
	v_cvt_pk_bf16_f32 v12, v12, v13
	v_cvt_pk_bf16_f32 v13, v14, v15
	global_store_dwordx2 v32, v[12:13], s[12:13]
	global_load_dwordx4 v[12:15], v[20:21], off offset:1024
	s_waitcnt vmcnt(0)
	v_pk_mul_f32 v[8:9], v[12:13], v[8:9]
	v_pk_mul_f32 v[10:11], v[14:15], v[10:11]
	v_cvt_pk_bf16_f32 v8, v8, v9
	v_cvt_pk_bf16_f32 v9, v10, v11
	global_store_dwordx2 v32, v[8:9], s[12:13] offset:512
	global_load_dwordx4 v[8:11], v[20:21], off offset:2048
	s_waitcnt vmcnt(0)
	v_pk_mul_f32 v[4:5], v[8:9], v[4:5]
	v_pk_mul_f32 v[6:7], v[10:11], v[6:7]
	v_cvt_pk_bf16_f32 v4, v4, v5
	v_cvt_pk_bf16_f32 v5, v6, v7
	global_store_dwordx2 v32, v[4:5], s[12:13] offset:1024
	global_load_dwordx4 v[4:7], v[20:21], off offset:3072
	s_waitcnt vmcnt(0)
	v_pk_mul_f32 v[0:1], v[0:1], v[4:5]
	v_pk_mul_f32 v[2:3], v[2:3], v[6:7]
	v_cvt_pk_bf16_f32 v0, v0, v1
	v_cvt_pk_bf16_f32 v1, v2, v3
	global_store_dwordx2 v32, v[0:1], s[12:13] offset:1536
	v_readlane_b32 s12, v254, 4
	v_readlane_b32 s13, v254, 5
	s_add_u32 s8, s8, s12
	s_addc_u32 s9, s9, s13
	s_cmpk_gt_i32 s10, 0x5ff
	s_cbranch_scc1 .LBB0_1064

; #define GAS __attribute__((address_space(1)))
; DI unsigned pk2(float lo, float hi) { f32x2 v = {lo, hi}; bf16x2_t b = __builtin_convertvector(v, bf16x2_t); return __builtin_bit_cast(unsigned, b); }
; DI void norm_row_bf16(const f32x4 (&v)[4], const float* g, bf16_t* orow, int lane) {
;     float s = 0.f;
; #pragma unroll
;     for (int j = 0; j < 4; ++j) s += (v[j].x * v[j].x + v[j].y * v[j].y) + (v[j].z * v[j].z + v[j].w * v[j].w);
;     const float rstd = __builtin_amdgcn_rsqf(wave_sum(s, lane) * (1.0f / DM) + RMS_EPS);
;     GAS u32x2* o8 = (GAS u32x2*)orow + lane;
; #pragma unroll
;     for (int j = 0; j < 4; ++j) { const f32x4 gg = ((const GAS f32x4*)g)[lane + 64 * j]; u32x2 w; w.x = pk2(v[j].x * rstd * gg.x, v[j].y * rstd * gg.y); w.y = pk2(v[j].z * rstd * gg.z, v[j].w * rstd * gg.w); o8[64 * j] = w; }
; }
; __global__ void __launch_bounds__(512) fwd_megakernel(Params p) {
;     ...
;                 for (int row = gw; row < NTOK; row += NGW) { const float* src = row < TOK_P ? x_p + (size_t)row * DM : x_s + (size_t)(row - TOK_P) * DM;
;                     f32x4 v[4];
; #pragma unroll
;                     for (int j = 0; j < 4; ++j) v[j] = ((const GAS f32x4*)src)[lane + 64 * j];
;                     norm_row_bf16(v, g_pre0, act + (size_t)row * DM, lane); }
.LBB0_1067:
	v_lshlrev_b32_e32 v0, 4, v16
	global_load_dwordx4 v[12:15], v0, s[8:9] nt
	global_load_dwordx4 v[8:11], v0, s[8:9] offset:1024 nt
	global_load_dwordx4 v[4:7], v0, s[8:9] offset:2048 nt
	s_nop 0
	global_load_dwordx4 v[0:3], v0, s[8:9] offset:3072 nt
	s_lshl_b64 s[8:9], s[10:11], 11
	s_add_u32 s8, s1, s8
	s_addc_u32 s9, s12, s9
	s_add_u32 s4, s4, s72
	s_addc_u32 s5, s5, s73
	s_waitcnt vmcnt(0)
	v_pk_mul_f32 v[28:29], v[14:15], v[14:15]
	v_pk_mul_f32 v[30:31], v[12:13], v[12:13]
	v_mul_f32_e32 v22, v4, v4
	v_pk_mov_b32 v[32:33], v[30:31], v[28:29] op_sel:[1,0]
	v_mov_b32_e32 v31, v29
	v_pk_add_f32 v[28:29], v[32:33], v[30:31]
	v_pk_mul_f32 v[30:31], v[10:11], v[10:11]
	v_pk_mul_f32 v[32:33], v[8:9], v[8:9]
	v_pk_add_f32 v[28:29], v[28:29], v[28:29] op_sel_hi:[0,1]
	v_pk_mov_b32 v[34:35], v[32:33], v[30:31] op_sel:[1,0]
	v_mov_b32_e32 v33, v31
	v_pk_add_f32 v[30:31], v[34:35], v[32:33]
	v_pk_fma_f32 v[32:33], v[4:5], v[4:5], v[22:23] op_sel_hi:[1,1,0]
	v_mul_f32_e32 v22, v6, v6
	v_pk_add_f32 v[30:31], v[30:31], v[30:31] op_sel_hi:[0,1]
	v_pk_fma_f32 v[34:35], v[6:7], v[6:7], v[22:23] op_sel_hi:[1,1,0]
	v_mul_f32_e32 v32, v0, v0
	v_mul_f32_e32 v34, v1, v1
	v_mul_f32_e32 v28, v2, v2
	v_mul_f32_e32 v30, v3, v3
	v_pk_add_f32 v[32:33], v[32:33], v[34:35]
	v_pk_add_f32 v[28:29], v[28:29], v[30:31]
	s_nop 0
	v_pk_add_f32 v[28:29], v[32:33], v[28:29]
	v_lshlrev_b32_e32 v32, 3, v16
	v_add_f32_e32 v22, v28, v29
	ds_bpermute_b32 v28, v19, v22
	s_waitcnt lgkmcnt(0)
	v_add_f32_e32 v22, v22, v28
	ds_bpermute_b32 v28, v23, v22
	s_waitcnt lgkmcnt(0)
	v_add_f32_e32 v22, v22, v28
	ds_bpermute_b32 v28, v24, v22
	s_waitcnt lgkmcnt(0)
	v_add_f32_e32 v22, v22, v28
	ds_bpermute_b32 v28, v25, v22
	s_waitcnt lgkmcnt(0)
	v_add_f32_e32 v22, v22, v28
	ds_bpermute_b32 v28, v26, v22
	s_waitcnt lgkmcnt(0)
	v_add_f32_e32 v22, v22, v28
	ds_bpermute_b32 v28, v27, v22
	s_waitcnt lgkmcnt(0)
	v_add_f32_e32 v22, v22, v28
	global_load_dwordx4 v[28:31], v[20:21], off
	v_fmamk_f32 v22, v22, 0x3a800000, v174
	v_rsq_f32_e32 v22, v22
	s_nop 0
	v_pk_mul_f32 v[12:13], v[12:13], v[22:23] op_sel_hi:[1,0]
	v_pk_mul_f32 v[14:15], v[14:15], v[22:23] op_sel_hi:[1,0]
	v_pk_mul_f32 v[8:9], v[8:9], v[22:23] op_sel_hi:[1,0]
	v_pk_mul_f32 v[10:11], v[10:11], v[22:23] op_sel_hi:[1,0]
	v_pk_mul_f32 v[4:5], v[4:5], v[22:23] op_sel_hi:[1,0]
	v_pk_mul_f32 v[6:7], v[6:7], v[22:23] op_sel_hi:[1,0]
	v_pk_mul_f32 v[0:1], v[0:1], v[22:23] op_sel_hi:[1,0]
	v_pk_mul_f32 v[2:3], v[2:3], v[22:23] op_sel_hi:[1,0]
	s_waitcnt vmcnt(0)
	v_pk_mul_f32 v[12:13], v[28:29], v[12:13]
	v_pk_mul_f32 v[14:15], v[30:31], v[14:15]
	v_cvt_pk_bf16_f32 v12, v12, v13
	v_cvt_pk_bf16_f32 v13, v14, v15
	global_store_dwordx2 v32, v[12:13], s[8:9]
	global_load_dwordx4 v[12:15], v[20:21], off offset:1024
	s_waitcnt vmcnt(0)
	v_pk_mul_f32 v[8:9], v[12:13], v[8:9]
	v_pk_mul_f32 v[10:11], v[14:15], v[10:11]
	v_cvt_pk_bf16_f32 v8, v8, v9
	v_cvt_pk_bf16_f32 v9, v10, v11
	global_store_dwordx2 v32, v[8:9], s[8:9] offset:512
	global_load_dwordx4 v[8:11], v[20:21], off offset:2048
	s_waitcnt vmcnt(0)
	v_pk_mul_f32 v[4:5], v[8:9], v[4:5]
	v_pk_mul_f32 v[6:7], v[10:11], v[6:7]
	v_cvt_pk_bf16_f32 v4, v4, v5
	v_cvt_pk_bf16_f32 v5, v6, v7
	global_store_dwordx2 v32, v[4:5], s[8:9] offset:1024
	global_load_dwordx4 v[4:7], v[20:21], off offset:3072
	s_waitcnt vmcnt(0)
	v_pk_mul_f32 v[0:1], v[0:1], v[4:5]
	v_pk_mul_f32 v[2:3], v[2:3], v[6:7]
	v_cvt_pk_bf16_f32 v0, v0, v1
	v_cvt_pk_bf16_f32 v1, v2, v3
	global_store_dwordx2 v32, v[0:1], s[8:9] offset:1536
	v_readlane_b32 s8, v254, 4
	v_readlane_b32 s9, v254, 5
	s_add_u32 s6, s6, s8
	s_addc_u32 s7, s7, s9
	s_cmp_gt_i32 s4, 0xbfff
	s_cbranch_scc1 .LBB0_1070
